# flat top-counter grid barrier + write-through P4/P5 stores (no L2 write-back at seams 4,5) on top of tile-group barriers
# speedup vs baseline: 1.0342x; 1.0038x over previous
.LBB0_90:
	s_or_b64 exec, exec, s[8:9]
	v_cvt_f32_u32_e32 v4, v2
	s_waitcnt vmcnt(0)
	v_readfirstlane_b32 s3, v3
	v_sub_u32_e32 v3, 0, v2
	v_rcp_iflag_f32_e32 v4, v4
	v_add_u32_e32 v5, s3, v1
	v_mul_f32_e32 v4, 0x4f7ffffe, v4
	v_cvt_u32_f32_e32 v4, v4
	v_mul_lo_u32 v1, v3, v4
	v_mul_hi_u32 v1, v4, v1
	v_add_u32_e32 v1, v4, v1
	v_mul_hi_u32 v1, v5, v1
	v_mul_lo_u32 v3, v1, v2
	v_sub_u32_e32 v3, v5, v3
	v_add_u32_e32 v4, 1, v1
	v_cmp_ge_u32_e32 vcc, v3, v2
	s_nop 1
	v_cndmask_b32_e32 v1, v1, v4, vcc
	v_sub_u32_e32 v4, v3, v2
	v_cndmask_b32_e32 v3, v3, v4, vcc
	v_add_u32_e32 v4, 1, v1
	v_cmp_ge_u32_e32 vcc, v3, v2
	v_add_u32_e32 v3, 1, v5
	s_nop 0
	v_cndmask_b32_e32 v1, v1, v4, vcc
	v_mul_lo_u32 v4, v2, v1
	v_add_u32_e32 v2, v4, v2
	v_cmp_ne_u32_e32 vcc, v3, v2
	s_cbranch_vccnz .Lmy_ft1_nl
	buffer_wbl2 sc1
	s_waitcnt vmcnt(0) lgkmcnt(0)
	v_mov_b32_e32 v2, 0x3000
	v_mov_b32_e32 v3, 1
	global_atomic_add v2, v3, s[52:53] offset:1024
.Lmy_ft1_nl:
	s_waitcnt lgkmcnt(0)
	v_add_u32_e32 v1, 1, v1
	v_mul_lo_u32 v1, v1, v0
	v_mov_b32_e32 v2, 0x3000
	s_mov_b32 s3, 0
.Lmy_ft1_poll:
	global_load_dword v3, v2, s[52:53] offset:1024 sc1
	s_waitcnt vmcnt(0)
	v_cmp_lt_u32_e32 vcc, v3, v1
	s_cbranch_vccz .Lmy_ft1_rdy
	s_sleep 0
	s_add_u32 s3, s3, 1
	s_cmp_lt_u32 s3, 0x40000
	s_cbranch_scc1 .Lmy_ft1_poll
.Lmy_ft1_rdy:
	buffer_inv sc1
	s_waitcnt vmcnt(0)
.LBB0_124:
	s_or_b64 exec, exec, s[0:1]
	s_waitcnt lgkmcnt(0)
	s_barrier

.LBB0_486:
	s_or_b64 exec, exec, s[20:21]
	v_cvt_f32_u32_e32 v7, v3
	s_waitcnt vmcnt(0)
	v_readfirstlane_b32 s14, v6
	v_sub_u32_e32 v6, 0, v3
	v_rcp_iflag_f32_e32 v7, v7
	v_add_u32_e32 v8, s14, v1
	v_mul_f32_e32 v7, 0x4f7ffffe, v7
	v_cvt_u32_f32_e32 v7, v7
	v_mul_lo_u32 v1, v6, v7
	v_mul_hi_u32 v1, v7, v1
	v_add_u32_e32 v1, v7, v1
	v_mul_hi_u32 v1, v8, v1
	v_mul_lo_u32 v6, v1, v3
	v_sub_u32_e32 v6, v8, v6
	v_add_u32_e32 v7, 1, v1
	v_cmp_ge_u32_e32 vcc, v6, v3
	s_nop 1
	v_cndmask_b32_e32 v1, v1, v7, vcc
	v_sub_u32_e32 v7, v6, v3
	v_cndmask_b32_e32 v6, v6, v7, vcc
	v_add_u32_e32 v7, 1, v1
	v_cmp_ge_u32_e32 vcc, v6, v3
	v_add_u32_e32 v6, 1, v8
	s_nop 0
	v_cndmask_b32_e32 v1, v1, v7, vcc
	v_mul_lo_u32 v7, v3, v1
	v_add_u32_e32 v3, v7, v3
	v_cmp_ne_u32_e32 vcc, v6, v3
	s_cbranch_vccnz .Lmy_ft4_nl
	s_waitcnt vmcnt(0) lgkmcnt(0)
	v_mov_b32_e32 v6, 0x3000
	v_mov_b32_e32 v7, 1
	global_atomic_add v6, v7, s[52:53] offset:1024
.Lmy_ft4_nl:
	s_waitcnt lgkmcnt(0)
	v_add_u32_e32 v1, 1, v1
	v_mul_lo_u32 v1, v1, v0
	v_mov_b32_e32 v6, 0x3000
	s_mov_b32 s14, 0
.Lmy_ft4_poll:
	global_load_dword v7, v6, s[52:53] offset:1024 sc1
	s_waitcnt vmcnt(0)
	v_cmp_lt_u32_e32 vcc, v7, v1
	s_cbranch_vccz .Lmy_ft4_rdy
	s_sleep 0
	s_add_u32 s14, s14, 1
	s_cmp_lt_u32 s14, 0x40000
	s_cbranch_scc1 .Lmy_ft4_poll
.Lmy_ft4_rdy:
	buffer_inv sc1
	s_waitcnt vmcnt(0)
.LBB0_520:
	s_or_b64 exec, exec, s[10:11]
	s_waitcnt lgkmcnt(0)
	s_barrier

.LBB0_706:
	s_or_b64 exec, exec, s[10:11]
	v_cvt_f32_u32_e32 v4, v2
	s_waitcnt vmcnt(0)
	v_readfirstlane_b32 s8, v3
	v_sub_u32_e32 v3, 0, v2
	v_rcp_iflag_f32_e32 v4, v4
	v_add_u32_e32 v5, s8, v1
	v_mul_f32_e32 v4, 0x4f7ffffe, v4
	v_cvt_u32_f32_e32 v4, v4
	v_mul_lo_u32 v1, v3, v4
	v_mul_hi_u32 v1, v4, v1
	v_add_u32_e32 v1, v4, v1
	v_mul_hi_u32 v1, v5, v1
	v_mul_lo_u32 v3, v1, v2
	v_sub_u32_e32 v3, v5, v3
	v_add_u32_e32 v4, 1, v1
	v_cmp_ge_u32_e32 vcc, v3, v2
	s_nop 1
	v_cndmask_b32_e32 v1, v1, v4, vcc
	v_sub_u32_e32 v4, v3, v2
	v_cndmask_b32_e32 v3, v3, v4, vcc
	v_add_u32_e32 v4, 1, v1
	v_cmp_ge_u32_e32 vcc, v3, v2
	v_add_u32_e32 v3, 1, v5
	s_nop 0
	v_cndmask_b32_e32 v1, v1, v4, vcc
	v_mul_lo_u32 v4, v2, v1
	v_add_u32_e32 v2, v4, v2
	v_cmp_ne_u32_e32 vcc, v3, v2
	s_cbranch_vccnz .Lmy_ft5_nl
	s_waitcnt vmcnt(0) lgkmcnt(0)
	v_mov_b32_e32 v2, 0x3000
	v_mov_b32_e32 v3, 1
	global_atomic_add v2, v3, s[52:53] offset:1024
.Lmy_ft5_nl:
	s_waitcnt lgkmcnt(0)
	v_add_u32_e32 v1, 1, v1
	v_mul_lo_u32 v1, v1, v0
	v_mov_b32_e32 v2, 0x3000
	s_mov_b32 s24, 0
.Lmy_ft5_poll:
	global_load_dword v3, v2, s[52:53] offset:1024 sc1
	s_waitcnt vmcnt(0)
	v_cmp_lt_u32_e32 vcc, v3, v1
	s_cbranch_vccz .Lmy_ft5_rdy
	s_sleep 0
	s_add_u32 s24, s24, 1
	s_cmp_lt_u32 s24, 0x40000
	s_cbranch_scc1 .Lmy_ft5_poll
.Lmy_ft5_rdy:
	buffer_inv sc1
	s_waitcnt vmcnt(0)
.LBB0_740:
	s_or_b64 exec, exec, s[0:1]
	s_waitcnt lgkmcnt(0)
	s_barrier
